# strategy 7: packed f32 ops split in the compress-tile K loop (A+pos adds feeding the MFMA A operand) and the ret_out tile
# speedup vs baseline: 1.0015x; 1.0008x over previous
.LBB0_633:
	v_lshl_add_u64 v[68:69], v[114:115], 0, s[88:89]
	global_load_dwordx4 v[70:73], v[68:69], off
	v_lshl_add_u64 v[66:67], s[8:9], 0, v[118:119]
	v_lshl_add_u64 v[114:115], v[114:115], 0, s[42:43]
	s_waitcnt vmcnt(0)
	v_lshlrev_b32_e32 v84, 16, v70
	v_and_b32_e32 v85, 0xffff0000, v70
	v_lshlrev_b32_e32 v86, 16, v71
	v_and_b32_e32 v87, 0xffff0000, v71
	v_lshl_add_u64 v[70:71], v[112:113], 0, s[88:89]
	v_lshlrev_b32_e32 v88, 16, v72
	v_and_b32_e32 v89, 0xffff0000, v72
	v_lshlrev_b32_e32 v90, 16, v73
	v_and_b32_e32 v91, 0xffff0000, v73
	global_load_dwordx4 v[72:75], v[70:71], off
	global_load_dwordx4 v[76:79], v[66:67], off offset:16
	global_load_dwordx4 v[80:83], v[66:67], off
	v_lshl_add_u64 v[112:113], v[112:113], 0, s[42:43]
	s_waitcnt vmcnt(2)
	v_lshlrev_b32_e32 v92, 16, v72
	v_and_b32_e32 v93, 0xffff0000, v72
	s_waitcnt vmcnt(0)
	v_add_f32_e64 v84, v80, v84
	v_add_f32_e64 v85, v81, v85
	v_lshlrev_b32_e32 v72, 16, v73
	v_and_b32_e32 v73, 0xffff0000, v73
	v_cvt_pk_bf16_f32 v130, v84, v85
	v_add_f32_e64 v84, v82, v86
	v_add_f32_e64 v85, v83, v87
	v_add_f32_e64 v72, v82, v72
	v_add_f32_e64 v73, v83, v73
	v_lshlrev_b32_e32 v82, 16, v74
	v_and_b32_e32 v83, 0xffff0000, v74
	v_lshlrev_b32_e32 v74, 16, v75
	v_and_b32_e32 v75, 0xffff0000, v75
	v_add_f32_e64 v74, v78, v74
	v_add_f32_e64 v75, v79, v75
	v_cvt_pk_bf16_f32 v131, v84, v85
	v_cvt_pk_bf16_f32 v137, v74, v75
	v_lshl_add_u64 v[74:75], v[106:107], 0, s[12:13]
	v_add_f32_e64 v84, v76, v88
	v_add_f32_e64 v85, v77, v89
	v_add_f32_e64 v76, v76, v82
	v_add_f32_e64 v77, v77, v83
	v_add_f32_e64 v82, v78, v90
	v_add_f32_e64 v83, v79, v91
	v_add_co_u32_e64 v78, s[0:1], s4, v74
	v_cvt_pk_bf16_f32 v133, v82, v83
	s_nop 0
	v_addc_co_u32_e64 v79, s[0:1], 0, v75, s[0:1]
	v_add_co_u32_e64 v82, s[0:1], s5, v74
	global_load_dwordx4 v[138:141], v[74:75], off
	global_load_dwordx4 v[142:145], v[78:79], off
	v_addc_co_u32_e64 v83, s[0:1], 0, v75, s[0:1]
	v_add_co_u32_e64 v86, s[0:1], s2, v74
	global_load_dwordx4 v[146:149], v[82:83], off
	s_nop 0
	v_addc_co_u32_e64 v87, s[0:1], 0, v75, s[0:1]
	v_add_co_u32_e64 v90, s[0:1], s20, v74
	global_load_dwordx4 v[150:153], v[86:87], off
	s_nop 0
	v_addc_co_u32_e64 v91, s[0:1], 0, v75, s[0:1]
	v_add_co_u32_e64 v94, s[0:1], s21, v74
	global_load_dwordx4 v[154:157], v[90:91], off
	s_nop 0
	v_addc_co_u32_e64 v95, s[0:1], 0, v75, s[0:1]
	v_add_co_u32_e64 v98, s[0:1], s38, v74
	global_load_dwordx4 v[158:161], v[94:95], off
	s_nop 0
	v_addc_co_u32_e64 v99, s[0:1], 0, v75, s[0:1]
	v_add_co_u32_e64 v102, s[0:1], s39, v74
	global_load_dwordx4 v[162:165], v[98:99], off
	s_nop 0
	v_addc_co_u32_e64 v103, s[0:1], 0, v75, s[0:1]
	global_load_dwordx4 v[166:169], v[102:103], off
	v_cvt_pk_bf16_f32 v132, v84, v85
	v_cvt_pk_bf16_f32 v136, v76, v77
	v_lshl_add_u64 v[76:77], v[122:123], 0, s[88:89]
	v_add_f32_e64 v80, v80, v92
	v_add_f32_e64 v81, v81, v93
	v_cvt_pk_bf16_f32 v135, v72, v73
	v_cvt_pk_bf16_f32 v134, v80, v81
	v_lshl_add_u64 v[72:73], s[8:9], 0, v[116:117]
	v_lshl_add_u64 v[92:93], v[120:121], 0, s[88:89]
	v_add_co_u32_e64 v68, s[0:1], s40, v68
	s_add_u32 s12, s12, 0x100
	s_nop 0
	v_addc_co_u32_e64 v69, s[0:1], 0, v69, s[0:1]
	s_addc_u32 s13, s13, 0
	v_lshl_add_u64 v[120:121], v[120:121], 0, s[42:43]
	v_lshl_add_u64 v[122:123], v[122:123], 0, s[42:43]
	s_waitcnt vmcnt(7)
	v_mfma_f32_16x16x32_bf16 v[62:65], v[130:133], v[138:141], v[62:65]
	s_waitcnt vmcnt(6)
	v_mfma_f32_16x16x32_bf16 v[58:61], v[130:133], v[142:145], v[58:61]
	s_waitcnt vmcnt(5)
	v_mfma_f32_16x16x32_bf16 v[54:57], v[130:133], v[146:149], v[54:57]
	s_waitcnt vmcnt(4)
	v_mfma_f32_16x16x32_bf16 v[50:53], v[130:133], v[150:153], v[50:53]
	s_waitcnt vmcnt(3)
	v_mfma_f32_16x16x32_bf16 v[46:49], v[130:133], v[154:157], v[46:49]
	s_waitcnt vmcnt(2)
	v_mfma_f32_16x16x32_bf16 v[42:45], v[130:133], v[158:161], v[42:45]
	s_waitcnt vmcnt(1)
	v_mfma_f32_16x16x32_bf16 v[38:41], v[130:133], v[162:165], v[38:41]
	s_waitcnt vmcnt(0)
	v_mfma_f32_16x16x32_bf16 v[34:37], v[130:133], v[166:169], v[34:37]
	global_load_dwordx4 v[130:133], v[76:77], off
	s_waitcnt vmcnt(0)
	v_lshlrev_b32_e32 v76, 16, v130
	v_mfma_f32_16x16x32_bf16 v[2:5], v[134:137], v[138:141], v[2:5]
	v_and_b32_e32 v77, 0xffff0000, v130
	v_lshlrev_b32_e32 v80, 16, v131
	v_and_b32_e32 v81, 0xffff0000, v131
	v_mfma_f32_16x16x32_bf16 v[6:9], v[134:137], v[142:145], v[6:9]
	v_lshlrev_b32_e32 v84, 16, v132
	v_and_b32_e32 v85, 0xffff0000, v132
	v_lshlrev_b32_e32 v88, 16, v133
	v_mfma_f32_16x16x32_bf16 v[10:13], v[134:137], v[146:149], v[10:13]
	v_and_b32_e32 v89, 0xffff0000, v133
	global_load_dwordx4 v[130:133], v[92:93], off
	s_waitcnt vmcnt(0)
	v_lshlrev_b32_e32 v92, 16, v130
	v_mfma_f32_16x16x32_bf16 v[14:17], v[134:137], v[150:153], v[14:17]
	v_and_b32_e32 v93, 0xffff0000, v130
	v_mfma_f32_16x16x32_bf16 v[18:21], v[134:137], v[154:157], v[18:21]
	v_mfma_f32_16x16x32_bf16 v[22:25], v[134:137], v[158:161], v[22:25]
	v_mfma_f32_16x16x32_bf16 v[26:29], v[134:137], v[162:165], v[26:29]
	v_mfma_f32_16x16x32_bf16 v[30:33], v[134:137], v[166:169], v[30:33]
	global_load_dwordx4 v[134:137], v[72:73], off offset:16
	global_load_dwordx4 v[138:141], v[72:73], off
	s_waitcnt vmcnt(1)
	v_add_f32_e64 v84, v134, v84
	v_add_f32_e64 v85, v135, v85
	s_waitcnt vmcnt(0)
	v_add_f32_e64 v72, v138, v76
	v_add_f32_e64 v73, v139, v77
	v_lshlrev_b32_e32 v76, 16, v131
	v_and_b32_e32 v77, 0xffff0000, v131
	v_cvt_pk_bf16_f32 v130, v72, v73
	v_add_f32_e64 v72, v138, v92
	v_add_f32_e64 v73, v139, v93
	v_add_f32_e64 v80, v140, v80
	v_add_f32_e64 v81, v141, v81
	v_add_f32_e64 v76, v140, v76
	v_add_f32_e64 v77, v141, v77
	global_load_dwordx4 v[138:141], v[74:75], off offset:64
	global_load_dwordx4 v[142:145], v[78:79], off offset:64
	global_load_dwordx4 v[146:149], v[82:83], off offset:64
	global_load_dwordx4 v[150:153], v[86:87], off offset:64
	global_load_dwordx4 v[154:157], v[90:91], off offset:64
	global_load_dwordx4 v[158:161], v[94:95], off offset:64
	global_load_dwordx4 v[162:165], v[98:99], off offset:64
	global_load_dwordx4 v[166:169], v[102:103], off offset:64
	v_add_f32_e64 v88, v136, v88
	v_add_f32_e64 v89, v137, v89
	v_cvt_pk_bf16_f32 v131, v80, v81
	v_lshlrev_b32_e32 v80, 16, v132
	v_and_b32_e32 v81, 0xffff0000, v132
	v_cvt_pk_bf16_f32 v132, v84, v85
	v_lshlrev_b32_e32 v84, 16, v133
	v_and_b32_e32 v85, 0xffff0000, v133
	v_cvt_pk_bf16_f32 v133, v88, v89
	v_add_f32_e64 v80, v134, v80
	v_add_f32_e64 v81, v135, v81
	v_add_f32_e64 v84, v136, v84
	v_add_f32_e64 v85, v137, v85
	s_waitcnt vmcnt(7)
	v_mfma_f32_16x16x32_bf16 v[62:65], v[130:133], v[138:141], v[62:65]
	v_cvt_pk_bf16_f32 v134, v72, v73
	v_cvt_pk_bf16_f32 v135, v76, v77
	v_cvt_pk_bf16_f32 v136, v80, v81
	s_waitcnt vmcnt(6)
	v_mfma_f32_16x16x32_bf16 v[58:61], v[130:133], v[142:145], v[58:61]
	v_cvt_pk_bf16_f32 v137, v84, v85
	s_waitcnt vmcnt(5)
	v_mfma_f32_16x16x32_bf16 v[54:57], v[130:133], v[146:149], v[54:57]
	s_waitcnt vmcnt(4)
	v_mfma_f32_16x16x32_bf16 v[50:53], v[130:133], v[150:153], v[50:53]
	s_waitcnt vmcnt(3)
	v_mfma_f32_16x16x32_bf16 v[46:49], v[130:133], v[154:157], v[46:49]
	s_waitcnt vmcnt(2)
	v_mfma_f32_16x16x32_bf16 v[42:45], v[130:133], v[158:161], v[42:45]
	s_waitcnt vmcnt(1)
	v_mfma_f32_16x16x32_bf16 v[38:41], v[130:133], v[162:165], v[38:41]
	s_waitcnt vmcnt(0)
	v_mfma_f32_16x16x32_bf16 v[34:37], v[130:133], v[166:169], v[34:37]
	global_load_dwordx4 v[130:133], v[68:69], off offset:3840
	v_add_co_u32_e64 v68, s[0:1], s40, v70
	v_mfma_f32_16x16x32_bf16 v[2:5], v[134:137], v[138:141], v[2:5]
	s_nop 0
	v_addc_co_u32_e64 v69, s[0:1], 0, v71, s[0:1]
	global_load_dwordx4 v[68:71], v[68:69], off offset:3840
	v_mfma_f32_16x16x32_bf16 v[6:9], v[134:137], v[142:145], v[6:9]
	s_waitcnt vmcnt(1)
	v_lshlrev_b32_e32 v72, 16, v130
	v_mfma_f32_16x16x32_bf16 v[10:13], v[134:137], v[146:149], v[10:13]
	v_and_b32_e32 v73, 0xffff0000, v130
	v_lshlrev_b32_e32 v76, 16, v131
	v_and_b32_e32 v77, 0xffff0000, v131
	v_mfma_f32_16x16x32_bf16 v[14:17], v[134:137], v[150:153], v[14:17]
	v_lshlrev_b32_e32 v80, 16, v132
	v_and_b32_e32 v81, 0xffff0000, v132
	v_lshlrev_b32_e32 v84, 16, v133
	v_mfma_f32_16x16x32_bf16 v[18:21], v[134:137], v[154:157], v[18:21]
	v_and_b32_e32 v85, 0xffff0000, v133
	s_waitcnt vmcnt(0)
	v_lshlrev_b32_e32 v88, 16, v68
	v_and_b32_e32 v89, 0xffff0000, v68
	v_mfma_f32_16x16x32_bf16 v[22:25], v[134:137], v[158:161], v[22:25]
	v_lshlrev_b32_e32 v68, 16, v69
	v_and_b32_e32 v69, 0xffff0000, v69
	v_mfma_f32_16x16x32_bf16 v[26:29], v[134:137], v[162:165], v[26:29]
	v_mfma_f32_16x16x32_bf16 v[30:33], v[134:137], v[166:169], v[30:33]
	global_load_dwordx4 v[130:133], v[66:67], off offset:272
	global_load_dwordx4 v[134:137], v[66:67], off offset:256
	s_waitcnt vmcnt(1)
	v_add_f32_e64 v84, v132, v84
	v_add_f32_e64 v85, v133, v85
	s_waitcnt vmcnt(0)
	v_add_f32_e64 v66, v134, v72
	v_add_f32_e64 v67, v135, v73
	v_add_f32_e64 v76, v136, v76
	v_add_f32_e64 v77, v137, v77
	v_cvt_pk_bf16_f32 v66, v66, v67
	v_add_f32_e64 v72, v134, v88
	v_add_f32_e64 v73, v135, v89
	v_cvt_pk_bf16_f32 v67, v76, v77
	v_add_f32_e64 v76, v136, v68
	v_add_f32_e64 v77, v137, v69
	v_lshlrev_b32_e32 v88, 16, v70
	v_and_b32_e32 v89, 0xffff0000, v70
	v_add_f32_e64 v68, v130, v80
	v_add_f32_e64 v69, v131, v81
	v_lshlrev_b32_e32 v70, 16, v71
	v_and_b32_e32 v71, 0xffff0000, v71
	v_cvt_pk_bf16_f32 v68, v68, v69
	v_add_f32_e64 v80, v130, v88
	v_add_f32_e64 v81, v131, v89
	v_cvt_pk_bf16_f32 v69, v84, v85
	v_add_f32_e64 v84, v132, v70
	v_add_f32_e64 v85, v133, v71
	global_load_dwordx4 v[130:133], v[74:75], off offset:128
	global_load_dwordx4 v[134:137], v[78:79], off offset:128
	global_load_dwordx4 v[138:141], v[82:83], off offset:128
	global_load_dwordx4 v[142:145], v[86:87], off offset:128
	global_load_dwordx4 v[146:149], v[90:91], off offset:128
	global_load_dwordx4 v[150:153], v[94:95], off offset:128
	global_load_dwordx4 v[154:157], v[98:99], off offset:128
	global_load_dwordx4 v[158:161], v[102:103], off offset:128
	s_waitcnt vmcnt(7)
	v_mfma_f32_16x16x32_bf16 v[62:65], v[66:69], v[130:133], v[62:65]
	v_cvt_pk_bf16_f32 v70, v72, v73
	v_cvt_pk_bf16_f32 v71, v76, v77
	v_cvt_pk_bf16_f32 v72, v80, v81
	s_waitcnt vmcnt(6)
	v_mfma_f32_16x16x32_bf16 v[58:61], v[66:69], v[134:137], v[58:61]
	v_cvt_pk_bf16_f32 v73, v84, v85
	v_lshl_add_u64 v[76:77], s[8:9], 0, v[0:1]
	s_add_u32 s8, s8, 0x200
	s_waitcnt vmcnt(5)
	v_mfma_f32_16x16x32_bf16 v[54:57], v[66:69], v[138:141], v[54:57]
	s_addc_u32 s9, s9, 0
	s_cmpk_eq_i32 s12, 0x400
	s_waitcnt vmcnt(4)
	v_mfma_f32_16x16x32_bf16 v[50:53], v[66:69], v[142:145], v[50:53]
	s_waitcnt vmcnt(3)
	v_mfma_f32_16x16x32_bf16 v[46:49], v[66:69], v[146:149], v[46:49]
	s_waitcnt vmcnt(2)
	v_mfma_f32_16x16x32_bf16 v[42:45], v[66:69], v[150:153], v[42:45]
	s_waitcnt vmcnt(1)
	v_mfma_f32_16x16x32_bf16 v[38:41], v[66:69], v[154:157], v[38:41]
	s_waitcnt vmcnt(0)
	v_mfma_f32_16x16x32_bf16 v[34:37], v[66:69], v[158:161], v[34:37]
	v_lshl_add_u64 v[66:67], v[110:111], 0, s[88:89]
	global_load_dwordx4 v[66:69], v[66:67], off
	v_lshl_add_u64 v[110:111], v[110:111], 0, s[42:43]
	v_mfma_f32_16x16x32_bf16 v[2:5], v[70:73], v[130:133], v[2:5]
	s_waitcnt vmcnt(0)
	v_lshlrev_b32_e32 v80, 16, v66
	v_and_b32_e32 v81, 0xffff0000, v66
	v_lshlrev_b32_e32 v84, 16, v67
	v_and_b32_e32 v85, 0xffff0000, v67
	v_lshl_add_u64 v[66:67], v[108:109], 0, s[88:89]
	v_mfma_f32_16x16x32_bf16 v[6:9], v[70:73], v[134:137], v[6:9]
	v_lshlrev_b32_e32 v88, 16, v68
	v_and_b32_e32 v89, 0xffff0000, v68
	v_lshlrev_b32_e32 v92, 16, v69
	v_mfma_f32_16x16x32_bf16 v[10:13], v[70:73], v[138:141], v[10:13]
	v_and_b32_e32 v93, 0xffff0000, v69
	global_load_dwordx4 v[66:69], v[66:67], off
	v_lshl_add_u64 v[108:109], v[108:109], 0, s[42:43]
	v_mfma_f32_16x16x32_bf16 v[14:17], v[70:73], v[142:145], v[14:17]
	s_waitcnt vmcnt(0)
	v_lshlrev_b32_e32 v96, 16, v66
	v_mfma_f32_16x16x32_bf16 v[18:21], v[70:73], v[146:149], v[18:21]
	v_and_b32_e32 v97, 0xffff0000, v66
	v_mfma_f32_16x16x32_bf16 v[22:25], v[70:73], v[150:153], v[22:25]
	v_mfma_f32_16x16x32_bf16 v[26:29], v[70:73], v[154:157], v[26:29]
	v_mfma_f32_16x16x32_bf16 v[30:33], v[70:73], v[158:161], v[30:33]
	global_load_dwordx4 v[70:73], v[76:77], off offset:16
	global_load_dwordx4 v[130:133], v[76:77], off
	s_waitcnt vmcnt(1)
	v_add_f32_e64 v88, v70, v88
	v_add_f32_e64 v89, v71, v89
	s_waitcnt vmcnt(0)
	v_add_f32_e64 v84, v132, v84
	v_add_f32_e64 v85, v133, v85
	v_add_f32_e64 v76, v130, v80
	v_add_f32_e64 v77, v131, v81
	v_lshlrev_b32_e32 v80, 16, v67
	v_and_b32_e32 v81, 0xffff0000, v67
	v_cvt_pk_bf16_f32 v67, v84, v85
	v_lshlrev_b32_e32 v84, 16, v68
	v_and_b32_e32 v85, 0xffff0000, v68
	v_cvt_pk_bf16_f32 v68, v88, v89
	v_add_f32_e64 v84, v70, v84
	v_add_f32_e64 v85, v71, v85
	v_lshlrev_b32_e32 v70, 16, v69
	v_and_b32_e32 v71, 0xffff0000, v69
	v_add_f32_e64 v88, v72, v92
	v_add_f32_e64 v89, v73, v93
	v_cvt_pk_bf16_f32 v66, v76, v77
	v_add_f32_e64 v76, v130, v96
	v_add_f32_e64 v77, v131, v97
	v_add_f32_e64 v80, v132, v80
	v_add_f32_e64 v81, v133, v81
	v_cvt_pk_bf16_f32 v69, v88, v89
	v_add_f32_e64 v88, v72, v70
	v_add_f32_e64 v89, v73, v71
	v_cvt_pk_bf16_f32 v70, v76, v77
	v_cvt_pk_bf16_f32 v71, v80, v81
	v_cvt_pk_bf16_f32 v72, v84, v85
	v_cvt_pk_bf16_f32 v73, v88, v89
	global_load_dwordx4 v[74:77], v[74:75], off offset:192
	s_nop 0
	global_load_dwordx4 v[78:81], v[78:79], off offset:192
	s_nop 0
	global_load_dwordx4 v[82:85], v[82:83], off offset:192
	s_nop 0
	global_load_dwordx4 v[86:89], v[86:87], off offset:192
	s_nop 0
	global_load_dwordx4 v[90:93], v[90:91], off offset:192
	s_nop 0
	global_load_dwordx4 v[94:97], v[94:95], off offset:192
	s_nop 0
	global_load_dwordx4 v[98:101], v[98:99], off offset:192
	s_nop 0
	global_load_dwordx4 v[102:105], v[102:103], off offset:192
	s_waitcnt vmcnt(7)
	v_mfma_f32_16x16x32_bf16 v[62:65], v[66:69], v[74:77], v[62:65]
	s_waitcnt vmcnt(6)
	v_mfma_f32_16x16x32_bf16 v[58:61], v[66:69], v[78:81], v[58:61]
	s_waitcnt vmcnt(5)
	v_mfma_f32_16x16x32_bf16 v[54:57], v[66:69], v[82:85], v[54:57]
	s_waitcnt vmcnt(4)
	v_mfma_f32_16x16x32_bf16 v[50:53], v[66:69], v[86:89], v[50:53]
	s_waitcnt vmcnt(3)
	v_mfma_f32_16x16x32_bf16 v[46:49], v[66:69], v[90:93], v[46:49]
	s_waitcnt vmcnt(2)
	v_mfma_f32_16x16x32_bf16 v[42:45], v[66:69], v[94:97], v[42:45]
	s_waitcnt vmcnt(1)
	v_mfma_f32_16x16x32_bf16 v[38:41], v[66:69], v[98:101], v[38:41]
	s_waitcnt vmcnt(0)
	v_mfma_f32_16x16x32_bf16 v[34:37], v[66:69], v[102:105], v[34:37]
	v_mfma_f32_16x16x32_bf16 v[2:5], v[70:73], v[74:77], v[2:5]
	v_mfma_f32_16x16x32_bf16 v[6:9], v[70:73], v[78:81], v[6:9]
	v_mfma_f32_16x16x32_bf16 v[10:13], v[70:73], v[82:85], v[10:13]
	v_mfma_f32_16x16x32_bf16 v[14:17], v[70:73], v[86:89], v[14:17]
	v_mfma_f32_16x16x32_bf16 v[18:21], v[70:73], v[90:93], v[18:21]
	v_mfma_f32_16x16x32_bf16 v[22:25], v[70:73], v[94:97], v[22:25]
	v_mfma_f32_16x16x32_bf16 v[26:29], v[70:73], v[98:101], v[26:29]
	v_mfma_f32_16x16x32_bf16 v[30:33], v[70:73], v[102:105], v[30:33]
	s_cbranch_scc0 .LBB0_633
	v_lshlrev_b32_e32 v66, 2, v126
	v_lshlrev_b32_e32 v0, 11, v125
	v_lshl_or_b32 v66, v124, 14, v66
	v_add3_u32 v0, s15, v0, v66
	ds_write2_b32 v0, v62, v58 offset1:16
	ds_write2_b32 v0, v63, v59 offset0:128 offset1:144
	v_add_u32_e32 v58, 0x400, v0
	ds_write2_b32 v58, v64, v60 offset1:16
	ds_write2_b32 v58, v65, v61 offset0:128 offset1:144
	ds_write2_b32 v0, v54, v50 offset0:32 offset1:48
	ds_write2_b32 v0, v55, v51 offset0:160 offset1:176
	ds_write2_b32 v58, v56, v52 offset0:32 offset1:48
	ds_write2_b32 v58, v57, v53 offset0:160 offset1:176
	ds_write2_b32 v0, v46, v42 offset0:64 offset1:80
	ds_write2_b32 v0, v47, v43 offset0:192 offset1:208
	ds_write2_b32 v58, v48, v44 offset0:64 offset1:80
	ds_write2_b32 v58, v49, v45 offset0:192 offset1:208
	ds_write2_b32 v0, v38, v34 offset0:96 offset1:112
	ds_write2_b32 v0, v39, v35 offset0:224 offset1:240
	ds_write2_b32 v58, v40, v36 offset0:96 offset1:112
	ds_write2_b32 v58, v41, v37 offset0:224 offset1:240
	v_add_u32_e32 v34, 0x2000, v0
	v_add_u32_e32 v0, 0x2400, v0
	s_add_i32 s2, s15, 0x10000
	s_movk_i32 s68, 0x1000
	ds_write2_b32 v34, v2, v6 offset1:16
	ds_write2_b32 v34, v3, v7 offset0:128 offset1:144
	ds_write2_b32 v0, v4, v8 offset1:16
	ds_write2_b32 v0, v5, v9 offset0:128 offset1:144
	ds_write2_b32 v34, v10, v14 offset0:32 offset1:48
	ds_write2_b32 v34, v11, v15 offset0:160 offset1:176
	ds_write2_b32 v0, v12, v16 offset0:32 offset1:48
	ds_write2_b32 v0, v13, v17 offset0:160 offset1:176
	ds_write2_b32 v34, v18, v22 offset0:64 offset1:80
	ds_write2_b32 v34, v19, v23 offset0:192 offset1:208
	ds_write2_b32 v0, v20, v24 offset0:64 offset1:80
	ds_write2_b32 v0, v21, v25 offset0:192 offset1:208
	ds_write2_b32 v34, v26, v30 offset0:96 offset1:112
	ds_write2_b32 v34, v27, v31 offset0:224 offset1:240
	ds_write2_b32 v0, v28, v32 offset0:96 offset1:112
	ds_write2_b32 v0, v29, v33 offset0:224 offset1:240
	v_lshl_add_u32 v0, v128, 1, s2
	v_lshl_add_u32 v2, v128, 2, s15
	v_or_b32_e32 v3, 0xffffff00, v128
	s_mov_b64 s[4:5], 0
	s_waitcnt lgkmcnt(0)
	s_barrier

.LBB0_1085:
	ds_read_b128 v[106:109], v129
	ds_read_b128 v[130:133], v129 offset:64
	s_add_i32 s2, s2, 32
	s_waitcnt vmcnt(1) lgkmcnt(1)
	v_mfma_f32_16x16x32_bf16 v[106:109], v[106:109], v[102:105], 0
	ds_read_b128 v[134:137], v129 offset:2368
	s_waitcnt vmcnt(0) lgkmcnt(1)
	v_mfma_f32_16x16x32_bf16 v[106:109], v[130:133], v[70:73], v[106:109]
	ds_read_b128 v[130:133], v129 offset:2304
	v_add_u32_e32 v129, 0x1200, v129
	s_waitcnt lgkmcnt(0)
	v_mfma_f32_16x16x32_bf16 v[130:133], v[130:133], v[102:105], 0
	s_nop 3
	v_mul_f32_e32 v106, 0x3e000000, v106
	v_mul_f32_e32 v107, 0x3e000000, v107
	v_mul_f32_e64 v108, v108, s18
	v_mul_f32_e64 v109, v109, s18
	v_mfma_f32_16x16x32_bf16 v[130:133], v[134:137], v[70:73], v[130:133]
	v_add_u32_e32 v135, v122, v112
	v_cvt_f32_u32_e32 v137, v135
	v_add_u32_e32 v136, -16, v135
	v_cmp_lt_i32_e32 vcc, -1, v135
	v_add_u32_e32 v134, s2, v114
	v_mul_f32_e32 v137, v115, v137
	v_mul_f32_e32 v137, 0x3fb8aa3b, v137
	v_exp_f32_e32 v137, v137
	v_subrev_u32_e32 v112, 32, v112
	v_mul_f32_e32 v106, v106, v137
	v_cndmask_b32_e32 v137, 0, v106, vcc
	v_mul_f32_e32 v106, 0x3e000000, v130
	v_cvt_f32_u32_e32 v130, v136
	v_cmp_lt_i32_e32 vcc, 15, v135
	v_mul_f32_e32 v130, v115, v130
	v_mul_f32_e32 v130, 0x3fb8aa3b, v130
	v_exp_f32_e32 v130, v130
	s_nop 0
	v_mul_f32_e32 v106, v130, v106
	v_cndmask_b32_e32 v136, 0, v106, vcc
	v_add_u32_e32 v106, -1, v135
	v_subrev_u32_e32 v130, 17, v135
	v_cvt_f32_u32_e32 v135, v106
	v_cmp_lt_i32_e32 vcc, -1, v106
	v_mul_f32_e32 v135, v115, v135
	v_mul_f32_e32 v135, 0x3fb8aa3b, v135
	v_exp_f32_e32 v135, v135
	s_nop 0
	v_mul_f32_e32 v107, v107, v135
	v_cndmask_b32_e32 v135, 0, v107, vcc
	v_cvt_f32_u32_e32 v107, v130
	v_cmp_lt_i32_e32 vcc, 15, v106
	v_mul_f32_e32 v106, 0x3e000000, v131
	v_mul_f32_e32 v107, v115, v107
	v_mul_f32_e32 v107, 0x3fb8aa3b, v107
	v_exp_f32_e32 v107, v107
	s_nop 0
	v_mul_f32_e32 v106, v107, v106
	v_or_b32_e32 v107, 2, v134
	v_cndmask_b32_e32 v138, 0, v106, vcc
	v_or_b32_e32 v106, 3, v134
	v_sub_u32_e32 v134, v110, v107
	v_add_u32_e32 v107, -16, v134
	v_cvt_f32_u32_e32 v107, v107
	v_sub_u32_e32 v131, v111, v106
	v_cvt_f32_u32_e32 v106, v134
	v_add_u32_e32 v139, -16, v131
	v_mul_f32_e32 v107, v115, v107
	v_mul_f32_e32 v107, 0x3fb8aa3b, v107
	v_exp_f32_e32 v130, v107
	v_cvt_f32_u32_e32 v107, v131
	v_cmp_lt_i32_e32 vcc, -1, v131
	v_cmp_lt_i32_e64 s[8:9], 15, v131
	v_cvt_f32_u32_e32 v131, v139
	v_mul_f32_e32 v106, v115, v106
	v_mul_f32_e32 v107, v115, v107
	v_mul_f32_e32 v106, 0x3fb8aa3b, v106
	v_mul_f32_e32 v107, 0x3fb8aa3b, v107
	v_mul_f32_e32 v131, v115, v131
	v_exp_f32_e32 v106, v106
	v_exp_f32_e32 v107, v107
	v_mul_f32_e32 v131, 0x3fb8aa3b, v131
	v_exp_f32_e32 v131, v131
	v_cmp_lt_i32_e64 s[10:11], 15, v134
	v_mul_f32_e64 v108, v108, v106
	v_mul_f32_e64 v109, v109, v107
	v_mul_f32_e64 v106, v132, s18
	v_mul_f32_e64 v107, v133, s18
	v_cmp_lt_i32_e64 s[0:1], -1, v134
	v_mul_f32_e64 v130, v130, v106
	v_mul_f32_e64 v131, v131, v107
	v_cvt_pk_bf16_f32 v107, v108, v109
	v_cvt_pk_bf16_f32 v109, v130, v131
	v_cndmask_b32_e64 v130, 0, v109, s[10:11]
	v_lshrrev_b32_e32 v109, 16, v109
	v_cndmask_b32_e64 v109, 0, v109, s[8:9]
	v_perm_b32 v109, v109, v130, s19
	ds_read2_b64 v[130:133], v113 offset1:4
	v_cndmask_b32_e64 v108, 0, v107, s[0:1]
	v_lshrrev_b32_e32 v107, 16, v107
	v_cndmask_b32_e32 v107, 0, v107, vcc
	v_cvt_pk_bf16_f32 v106, v137, v135
	v_perm_b32 v107, v107, v108, s19
	v_cvt_pk_bf16_f32 v108, v136, v138
	v_cmp_eq_u32_e32 vcc, s2, v122
	s_or_b64 s[16:17], vcc, s[16:17]
	s_waitcnt lgkmcnt(0)
	v_mfma_f32_16x16x32_bf16 v[98:101], v[130:133], v[106:109], v[98:101]
	v_add_u32_e32 v130, 0x1000, v113
	ds_read2_b64 v[130:133], v130 offset0:32 offset1:36
	s_waitcnt lgkmcnt(0)
	v_mfma_f32_16x16x32_bf16 v[82:85], v[130:133], v[106:109], v[82:85]
	v_add_u32_e32 v130, 0x2000, v113
	ds_read2_b64 v[130:133], v130 offset0:64 offset1:68
	s_waitcnt lgkmcnt(0)
	v_mfma_f32_16x16x32_bf16 v[74:77], v[130:133], v[106:109], v[74:77]
	v_add_u32_e32 v130, 0x3000, v113
	ds_read2_b64 v[130:133], v130 offset0:96 offset1:100
	s_waitcnt lgkmcnt(0)
	v_mfma_f32_16x16x32_bf16 v[66:69], v[130:133], v[106:109], v[66:69]
	v_add_u32_e32 v130, 0x4000, v113
	ds_read2_b64 v[130:133], v130 offset0:128 offset1:132
	s_waitcnt lgkmcnt(0)
	v_mfma_f32_16x16x32_bf16 v[90:93], v[130:133], v[106:109], v[90:93]
	v_add_u32_e32 v130, 0x5000, v113
	ds_read2_b64 v[130:133], v130 offset0:160 offset1:164
	s_waitcnt lgkmcnt(0)
	v_mfma_f32_16x16x32_bf16 v[94:97], v[130:133], v[106:109], v[94:97]
	v_add_u32_e32 v130, 0x6000, v113
	ds_read2_b64 v[130:133], v130 offset0:192 offset1:196
	s_waitcnt lgkmcnt(0)
	v_mfma_f32_16x16x32_bf16 v[86:89], v[130:133], v[106:109], v[86:89]
	v_add_u32_e32 v130, 0x7000, v113
	ds_read2_b64 v[130:133], v130 offset0:224 offset1:228
	v_add_u32_e32 v113, 64, v113
	s_waitcnt lgkmcnt(0)
	v_mfma_f32_16x16x32_bf16 v[78:81], v[130:133], v[106:109], v[78:81]
	s_andn2_b64 exec, exec, s[16:17]
	s_cbranch_execnz .LBB0_1085
	s_or_b64 exec, exec, s[16:17]
	v_add_u32_e32 v106, 1, v110
	v_cvt_f32_u32_e32 v107, v106
	v_lshlrev_b32_e32 v106, 16, v102
	s_mov_b32 s13, s89
	s_brev_b32 s0, 60
	v_mul_f32_e32 v107, v115, v107
	v_mul_f32_e32 v107, 0x3fb8aa3b, v107
	v_exp_f32_e32 v108, v107
	v_and_b32_e32 v107, 0xffff0000, v102
	v_lshlrev_b32_e32 v102, 16, v103
	v_and_b32_e32 v103, 0xffff0000, v103
	v_mul_f32_e64 v102, v108, v102
	v_mul_f32_e64 v103, v108, v103
	v_cvt_pk_bf16_f32 v131, v102, v103
	v_lshlrev_b32_e32 v102, 16, v104
	v_and_b32_e32 v103, 0xffff0000, v104
	v_mul_f32_e64 v102, v108, v102
	v_mul_f32_e64 v103, v108, v103
	v_cvt_pk_bf16_f32 v132, v102, v103
	v_lshlrev_b32_e32 v102, 16, v105
	v_and_b32_e32 v103, 0xffff0000, v105
	v_mul_f32_e64 v102, v108, v102
	v_mul_f32_e64 v103, v108, v103
	v_cvt_pk_bf16_f32 v133, v102, v103
	v_lshlrev_b32_e32 v102, 16, v70
	v_and_b32_e32 v103, 0xffff0000, v70
	v_lshlrev_b32_e32 v70, 16, v71
	v_and_b32_e32 v71, 0xffff0000, v71
	v_mul_f32_e64 v106, v108, v106
	v_mul_f32_e64 v107, v108, v107
	v_mul_f32_e64 v70, v108, v70
	v_mul_f32_e64 v71, v108, v71
	v_cvt_pk_bf16_f32 v130, v106, v107
	v_cvt_pk_bf16_f32 v135, v70, v71
	v_lshlrev_b32_e32 v70, 16, v72
	v_and_b32_e32 v71, 0xffff0000, v72
	v_mul_f32_e64 v70, v108, v70
	v_mul_f32_e64 v71, v108, v71
	v_mfma_f32_16x16x32_bf16 v[98:101], v[2:5], v[130:133], v[98:101]
	v_cvt_pk_bf16_f32 v136, v70, v71
	v_lshlrev_b32_e32 v70, 16, v73
	v_and_b32_e32 v71, 0xffff0000, v73
	v_mfma_f32_16x16x32_bf16 v[66:69], v[26:29], v[130:133], v[66:69]
	v_mul_f32_e64 v102, v108, v102
	v_mul_f32_e64 v103, v108, v103
	v_mul_f32_e64 v70, v108, v70
	v_mul_f32_e64 v71, v108, v71
	v_cvt_pk_bf16_f32 v134, v102, v103
	v_cvt_pk_bf16_f32 v137, v70, v71
	v_mfma_f32_16x16x32_bf16 v[70:73], v[10:13], v[130:133], v[82:85]
	s_mov_b32 s2, 16
	v_mfma_f32_16x16x32_bf16 v[110:113], v[6:9], v[134:137], v[98:101]
	v_mfma_f32_16x16x32_bf16 v[98:101], v[30:33], v[134:137], v[66:69]
	v_mfma_f32_16x16x32_bf16 v[66:69], v[34:37], v[130:133], v[90:93]
	s_nop 5
	v_mul_f32_e32 v129, v111, v111
	v_fmac_f32_e32 v129, v110, v110
	v_fmac_f32_e32 v129, v112, v112
	v_mfma_f32_16x16x32_bf16 v[82:85], v[38:41], v[134:137], v[66:69]
	v_fmac_f32_e32 v129, v113, v113
	v_mfma_f32_16x16x32_bf16 v[66:69], v[42:45], v[130:133], v[94:97]
	v_mfma_f32_16x16x32_bf16 v[106:109], v[14:17], v[134:137], v[70:73]
	v_mfma_f32_16x16x32_bf16 v[70:73], v[18:21], v[130:133], v[74:77]
	v_mfma_f32_16x16x32_bf16 v[74:77], v[46:49], v[134:137], v[66:69]
	s_nop 5
	v_fmac_f32_e32 v129, v106, v106
	v_fmac_f32_e32 v129, v107, v107
	v_fmac_f32_e32 v129, v108, v108
	v_mfma_f32_16x16x32_bf16 v[66:69], v[50:53], v[130:133], v[86:89]
	v_fmac_f32_e32 v129, v109, v109
	v_mfma_f32_16x16x32_bf16 v[102:105], v[22:25], v[134:137], v[70:73]
	s_nop 2
	v_add_f32_e32 v70, 0, v110
	v_add_f32_e32 v86, v111, v70
	v_mfma_f32_16x16x32_bf16 v[70:73], v[54:57], v[134:137], v[66:69]
	s_nop 1
	v_fmac_f32_e32 v129, v102, v102
	v_fmac_f32_e32 v129, v103, v103
	v_fmac_f32_e32 v129, v104, v104
	v_add_f32_e32 v66, v112, v86
	v_add_f32_e32 v86, v113, v66
	v_mfma_f32_16x16x32_bf16 v[66:69], v[58:61], v[130:133], v[78:81]
	v_fmac_f32_e32 v129, v105, v105
	v_fmac_f32_e32 v129, v98, v98
	v_fmac_f32_e32 v129, v99, v99
	v_add_f32_e32 v78, v86, v106
	v_add_f32_e32 v78, v107, v78
	v_add_f32_e32 v78, v108, v78
	v_add_f32_e32 v78, v109, v78
	v_add_f32_e32 v78, v78, v102
	v_add_f32_e32 v78, v103, v78
	v_add_f32_e32 v78, v104, v78
	v_add_f32_e32 v78, v105, v78
	v_add_f32_e32 v78, v78, v98
	v_add_f32_e32 v90, v99, v78
	v_lshl_add_u64 v[78:79], v[120:121], 0, s[12:13]
	v_lshlrev_b32_e32 v80, 1, v114
	v_mov_b32_e32 v81, v1
	v_lshl_add_u64 v[86:87], v[78:79], 0, v[80:81]
	v_add_co_u32_e32 v96, vcc, s68, v86
	v_add_f32_e32 v78, v100, v90
	s_nop 0
	v_addc_co_u32_e32 v97, vcc, 0, v87, vcc
	global_load_dwordx2 v[88:89], v[96:97], off
	v_add_f32_e32 v78, v101, v78
	v_add_f32_e32 v78, v78, v82
	v_add_f32_e32 v78, v83, v78
	v_add_f32_e32 v78, v84, v78
	v_add_f32_e32 v90, v85, v78
	global_load_dwordx4 v[78:81], v[116:117], off
	global_load_dwordx4 v[92:95], v[118:119], off
	v_fmac_f32_e32 v129, v100, v100
	v_fmac_f32_e32 v129, v101, v101
	v_fmac_f32_e32 v129, v82, v82
	v_fmac_f32_e32 v129, v83, v83
	v_add_f32_e32 v120, v90, v74
	v_pk_mov_b32 v[90:91], v[84:85], v[74:75] op_sel:[1,0]
	v_fmac_f32_e32 v129, v84, v84
	v_mul_f32_e64 v90, v90, v90
	v_mul_f32_e64 v91, v91, v91
	v_mfma_f32_16x16x32_bf16 v[66:69], v[62:65], v[134:137], v[66:69]
	v_add_f32_e32 v90, v90, v129
	v_add_f32_e32 v129, v90, v91
	v_add_f32_e32 v90, v75, v120
	v_add_f32_e32 v130, v76, v90
	v_mul_f32_e64 v90, v76, v76
	v_mul_f32_e64 v91, v77, v77
	v_mul_f32_e64 v120, v74, v74
	v_mul_f32_e64 v121, v75, v75
	s_nop 0
	v_add_f32_e32 v91, v121, v129
	v_add_f32_e32 v120, v90, v91
	v_add_f32_e32 v90, v77, v130
	v_add_f32_e32 v121, v90, v70
	v_pk_mov_b32 v[90:91], v[76:77], v[70:71] op_sel:[1,0]
	s_nop 0
	v_mul_f32_e64 v90, v90, v90
	v_mul_f32_e64 v91, v91, v91
	s_nop 0
	v_add_f32_e32 v90, v90, v120
	v_add_f32_e32 v129, v90, v91
	v_add_f32_e32 v90, v71, v121
	v_add_f32_e32 v130, v72, v90
	v_mul_f32_e64 v90, v72, v72
	v_mul_f32_e64 v91, v73, v73
	v_mul_f32_e64 v120, v70, v70
	v_mul_f32_e64 v121, v71, v71
	s_nop 0
	v_add_f32_e32 v91, v121, v129
	v_add_f32_e32 v120, v90, v91
	v_add_f32_e32 v90, v73, v130
	v_add_f32_e32 v121, v90, v66
	v_pk_mov_b32 v[90:91], v[72:73], v[66:67] op_sel:[1,0]
	v_mul_f32_e64 v130, v66, v66
	v_mul_f32_e64 v131, v67, v67
	v_mul_f32_e64 v90, v90, v90
	v_mul_f32_e64 v91, v91, v91
	s_waitcnt vmcnt(2)
	v_lshlrev_b32_e32 v130, 16, v88
	v_add_f32_e32 v90, v90, v120
	v_add_f32_e32 v90, v90, v91
	v_add_f32_e32 v91, v67, v121
	v_mul_f32_e64 v120, v68, v68
	v_mul_f32_e64 v121, v69, v69
	v_add_f32_e32 v90, v131, v90
	v_add_f32_e32 v91, v68, v91
	v_add_f32_e32 v120, v120, v90
	v_mul_f32_e32 v90, v69, v69
	v_mov_b32_e32 v121, v69
	v_add_f32_e64 v90, v120, v90
	v_add_f32_e64 v91, v121, v91
	ds_bpermute_b32 v121, v123, v91
	ds_bpermute_b32 v120, v123, v90
	v_and_b32_e32 v131, 0xffff0000, v88
	v_mul_f32_e32 v88, 0xbfb8aa3b, v130
	v_exp_f32_e32 v133, v88
	v_mul_f32_e32 v88, 0xbfb8aa3b, v131
	s_waitcnt lgkmcnt(0)
	v_add_f32_e64 v90, v90, v120
	v_add_f32_e64 v91, v91, v121
	ds_bpermute_b32 v121, v124, v91
	ds_bpermute_b32 v120, v124, v90
	v_exp_f32_e32 v134, v88
	s_waitcnt lgkmcnt(0)
	v_add_f32_e64 v90, v90, v120
	v_add_f32_e64 v91, v91, v121
	s_nop 0
	v_mul_f32_e64 v90, v90, s0
	v_mul_f32_e64 v91, v91, s0
	s_mov_b64 s[0:1], 0x1000
	v_fma_f32 v120, -v91, v91, v90
	v_max_f32_e32 v120, 0, v120
	v_add_f32_e32 v120, 0x358637bd, v120
	v_mul_f32_e32 v121, 0x4b800000, v120
	v_cmp_gt_f32_e32 vcc, s69, v120
	v_add_f32_e64 v110, v110, -v91
	v_add_f32_e64 v111, v111, -v91
	v_lshl_add_u64 v[86:87], v[86:87], 0, s[0:1]
	v_cndmask_b32_e32 v120, v120, v121, vcc
	v_rsq_f32_e32 v129, v120
	global_load_dwordx2 v[120:121], v[86:87], off offset:32
	v_add_f32_e64 v112, v112, -v91
	v_add_f32_e64 v113, v113, -v91
	v_add_f32_e64 v106, v106, -v91
	v_add_f32_e64 v107, v107, -v91
	v_mul_f32_e32 v132, 0x45800000, v129
	v_cndmask_b32_e32 v88, v129, v132, vcc
	v_add_f32_e32 v129, 1.0, v133
	v_rcp_f32_e32 v132, v129
	v_add_f32_e32 v129, 1.0, v134
	v_rcp_f32_e32 v133, v129
	v_mul_f32_e64 v110, v110, v88
	v_mul_f32_e64 v111, v111, v88
	v_add_f32_e64 v102, v102, -v91
	v_add_f32_e64 v103, v103, -v91
	s_waitcnt vmcnt(1)
	v_fma_f32 v78, v78, v110, v92
	v_fma_f32 v79, v79, v111, v93
	v_mul_f32_e64 v92, v132, v130
	v_mul_f32_e64 v93, v133, v131
	v_add_f32_e64 v104, v104, -v91
	v_add_f32_e64 v105, v105, -v91
	v_mul_f32_e64 v78, v92, v78
	v_mul_f32_e64 v79, v93, v79
	v_lshlrev_b32_e32 v92, 16, v89
	v_and_b32_e32 v93, 0xffff0000, v89
	v_mul_f32_e32 v89, 0xbfb8aa3b, v92
	v_exp_f32_e32 v89, v89
	v_mul_f32_e32 v110, 0xbfb8aa3b, v93
	v_exp_f32_e32 v111, v110
	v_cvt_pk_bf16_f32 v78, v78, v79
	v_add_f32_e32 v79, 1.0, v89
	v_rcp_f32_e32 v110, v79
	v_add_f32_e32 v79, 1.0, v111
	v_rcp_f32_e32 v111, v79
	v_mul_f32_e64 v112, v112, v88
	v_mul_f32_e64 v113, v113, v88
	v_add_f32_e64 v98, v98, -v91
	v_add_f32_e64 v99, v99, -v91
	v_fma_f32 v80, v80, v112, v94
	v_fma_f32 v81, v81, v113, v95
	v_mul_f32_e64 v92, v110, v92
	v_mul_f32_e64 v93, v111, v93
	v_add_f32_e64 v100, v100, -v91
	v_add_f32_e64 v101, v101, -v91
	v_mul_f32_e64 v80, v92, v80
	v_mul_f32_e64 v81, v93, v81
	v_add_f32_e64 v82, v82, -v91
	v_add_f32_e64 v83, v83, -v91
	v_cvt_pk_bf16_f32 v79, v80, v81
	global_store_dwordx2 v[96:97], v[78:79], off
	global_load_dwordx4 v[78:81], v[116:117], off offset:64
	s_nop 0
	global_load_dwordx4 v[92:95], v[118:119], off offset:64
	v_add_f32_e64 v84, v84, -v91
	v_add_f32_e64 v85, v85, -v91
	v_add_f32_e64 v74, v74, -v91
	v_add_f32_e64 v75, v75, -v91
	v_add_f32_e64 v76, v76, -v91
	v_add_f32_e64 v77, v77, -v91
	v_add_f32_e64 v70, v70, -v91
	v_add_f32_e64 v71, v71, -v91
	v_add_f32_e64 v72, v72, -v91
	v_add_f32_e64 v73, v73, -v91
	v_add_f32_e64 v66, v66, -v91
	v_add_f32_e64 v67, v67, -v91
	v_add_f32_e64 v68, v68, -v91
	v_add_f32_e64 v69, v69, -v91
	s_mov_b64 s[0:1], 0
	s_and_b64 vcc, exec, s[14:15]
	s_waitcnt vmcnt(3)
	v_lshlrev_b32_e32 v96, 16, v120
	v_and_b32_e32 v97, 0xffff0000, v120
	v_mul_f32_e32 v89, 0xbfb8aa3b, v96
	v_exp_f32_e32 v89, v89
	v_mul_f32_e32 v110, 0xbfb8aa3b, v97
	v_exp_f32_e32 v113, v110
	global_load_dwordx2 v[110:111], v[86:87], off offset:64
	v_add_f32_e32 v89, 1.0, v89
	v_rcp_f32_e32 v112, v89
	v_add_f32_e32 v89, 1.0, v113
	v_rcp_f32_e32 v113, v89
	v_mul_f32_e64 v106, v106, v88
	v_mul_f32_e64 v107, v107, v88
	s_waitcnt vmcnt(1)
	v_fma_f32 v78, v106, v78, v92
	v_fma_f32 v79, v107, v79, v93
	v_mul_f32_e64 v92, v112, v96
	v_mul_f32_e64 v93, v113, v97
	v_add_f32_e64 v106, v108, -v91
	v_add_f32_e64 v107, v109, -v91
	v_mul_f32_e64 v78, v92, v78
	v_mul_f32_e64 v79, v93, v79
	v_lshlrev_b32_e32 v92, 16, v121
	v_and_b32_e32 v93, 0xffff0000, v121
	v_mul_f32_e32 v89, 0xbfb8aa3b, v92
	v_exp_f32_e32 v89, v89
	v_mul_f32_e32 v96, 0xbfb8aa3b, v93
	v_exp_f32_e32 v97, v96
	v_cvt_pk_bf16_f32 v78, v78, v79
	v_add_f32_e32 v79, 1.0, v89
	v_rcp_f32_e32 v96, v79
	v_add_f32_e32 v79, 1.0, v97
	v_rcp_f32_e32 v97, v79
	v_mul_f32_e64 v106, v106, v88
	v_mul_f32_e64 v107, v107, v88
	v_mul_f32_e64 v92, v96, v92
	v_mul_f32_e64 v93, v97, v93
	v_fma_f32 v80, v106, v80, v94
	v_fma_f32 v81, v107, v81, v95
	s_waitcnt vmcnt(0)
	v_lshlrev_b32_e32 v106, 16, v110
	v_mul_f32_e64 v80, v92, v80
	v_mul_f32_e64 v81, v93, v81
	v_and_b32_e32 v107, 0xffff0000, v110
	v_cvt_pk_bf16_f32 v79, v80, v81
	global_store_dwordx2 v[86:87], v[78:79], off offset:32
	global_load_dwordx4 v[78:81], v[116:117], off offset:128
	s_nop 0
	global_load_dwordx4 v[92:95], v[118:119], off offset:128
	global_load_dwordx2 v[96:97], v[86:87], off offset:96
	v_lshlrev_b32_e32 v108, 16, v111
	v_and_b32_e32 v109, 0xffff0000, v111
	v_mul_f32_e32 v89, 0xbfb8aa3b, v106
	v_mul_f32_e32 v110, 0xbfb8aa3b, v107
	v_mul_f32_e32 v111, 0xbfb8aa3b, v108
	v_mul_f32_e32 v112, 0xbfb8aa3b, v109
	v_exp_f32_e32 v89, v89
	v_exp_f32_e32 v110, v110
	v_exp_f32_e32 v111, v111
	v_exp_f32_e32 v112, v112
	v_add_f32_e32 v89, 1.0, v89
	v_add_f32_e32 v113, 1.0, v110
	v_add_f32_e32 v120, 1.0, v111
	v_add_f32_e32 v121, 1.0, v112
	v_rcp_f32_e32 v110, v89
	v_rcp_f32_e32 v111, v113
	v_rcp_f32_e32 v112, v120
	v_rcp_f32_e32 v113, v121
	v_mul_f32_e64 v102, v102, v88
	v_mul_f32_e64 v103, v103, v88
	v_mul_f32_e64 v104, v104, v88
	v_mul_f32_e64 v105, v105, v88
	v_mul_f32_e64 v106, v110, v106
	v_mul_f32_e64 v107, v111, v107
	v_mul_f32_e64 v108, v112, v108
	v_mul_f32_e64 v109, v113, v109
	s_waitcnt vmcnt(1)
	v_fma_f32 v78, v102, v78, v92
	v_fma_f32 v79, v103, v79, v93
	v_fma_f32 v80, v104, v80, v94
	v_fma_f32 v81, v105, v81, v95
	v_mul_f32_e64 v78, v106, v78
	v_mul_f32_e64 v79, v107, v79
	v_mul_f32_e64 v80, v108, v80
	v_mul_f32_e64 v81, v109, v81
	v_cvt_pk_bf16_f32 v78, v78, v79
	v_cvt_pk_bf16_f32 v79, v80, v81
	global_store_dwordx2 v[86:87], v[78:79], off offset:64
	global_load_dwordx4 v[78:81], v[116:117], off offset:192
	s_nop 0
	global_load_dwordx4 v[92:95], v[118:119], off offset:192
	global_load_dwordx2 v[102:103], v[86:87], off offset:128
	s_waitcnt vmcnt(4)
	v_lshlrev_b32_e32 v104, 16, v96
	v_and_b32_e32 v105, 0xffff0000, v96
	v_lshlrev_b32_e32 v96, 16, v97
	v_and_b32_e32 v97, 0xffff0000, v97
	v_mul_f32_e32 v89, 0xbfb8aa3b, v104
	v_mul_f32_e32 v106, 0xbfb8aa3b, v105
	v_mul_f32_e32 v107, 0xbfb8aa3b, v96
	v_mul_f32_e32 v108, 0xbfb8aa3b, v97
	v_exp_f32_e32 v89, v89
	v_exp_f32_e32 v106, v106
	v_exp_f32_e32 v107, v107
	v_exp_f32_e32 v108, v108
	v_add_f32_e32 v89, 1.0, v89
	v_add_f32_e32 v109, 1.0, v106
	v_add_f32_e32 v110, 1.0, v107
	v_add_f32_e32 v111, 1.0, v108
	v_rcp_f32_e32 v106, v89
	v_rcp_f32_e32 v107, v109
	v_rcp_f32_e32 v108, v110
	v_rcp_f32_e32 v109, v111
	v_mul_f32_e64 v98, v98, v88
	v_mul_f32_e64 v99, v99, v88
	v_mul_f32_e64 v100, v100, v88
	v_mul_f32_e64 v101, v101, v88
	v_mul_f32_e64 v104, v106, v104
	v_mul_f32_e64 v105, v107, v105
	v_mul_f32_e64 v96, v108, v96
	v_mul_f32_e64 v97, v109, v97
	s_waitcnt vmcnt(1)
	v_fma_f32 v78, v98, v78, v92
	v_fma_f32 v79, v99, v79, v93
	v_fma_f32 v80, v100, v80, v94
	v_fma_f32 v81, v101, v81, v95
	v_mul_f32_e64 v78, v104, v78
	v_mul_f32_e64 v79, v105, v79
	v_mul_f32_e64 v80, v96, v80
	v_mul_f32_e64 v81, v97, v81
	v_cvt_pk_bf16_f32 v78, v78, v79
	v_cvt_pk_bf16_f32 v79, v80, v81
	global_store_dwordx2 v[86:87], v[78:79], off offset:96
	global_load_dwordx4 v[78:81], v[116:117], off offset:256
	s_nop 0
	global_load_dwordx4 v[92:95], v[118:119], off offset:256
	global_load_dwordx2 v[96:97], v[86:87], off offset:160
	s_waitcnt vmcnt(4)
	v_lshlrev_b32_e32 v98, 16, v102
	v_and_b32_e32 v99, 0xffff0000, v102
	v_lshlrev_b32_e32 v100, 16, v103
	v_and_b32_e32 v101, 0xffff0000, v103
	v_mul_f32_e32 v89, 0xbfb8aa3b, v98
	v_mul_f32_e32 v102, 0xbfb8aa3b, v99
	v_mul_f32_e32 v103, 0xbfb8aa3b, v100
	v_mul_f32_e32 v104, 0xbfb8aa3b, v101
	v_exp_f32_e32 v89, v89
	v_exp_f32_e32 v102, v102
	v_exp_f32_e32 v103, v103
	v_exp_f32_e32 v104, v104
	v_add_f32_e32 v89, 1.0, v89
	v_add_f32_e32 v105, 1.0, v102
	v_add_f32_e32 v106, 1.0, v103
	v_add_f32_e32 v107, 1.0, v104
	v_rcp_f32_e32 v102, v89
	v_rcp_f32_e32 v103, v105
	v_rcp_f32_e32 v104, v106
	v_rcp_f32_e32 v105, v107
	v_mul_f32_e64 v82, v82, v88
	v_mul_f32_e64 v83, v83, v88
	v_mul_f32_e64 v84, v84, v88
	v_mul_f32_e64 v85, v85, v88
	v_mul_f32_e64 v98, v102, v98
	v_mul_f32_e64 v99, v103, v99
	v_mul_f32_e64 v100, v104, v100
	v_mul_f32_e64 v101, v105, v101
	s_waitcnt vmcnt(1)
	v_fma_f32 v78, v82, v78, v92
	v_fma_f32 v79, v83, v79, v93
	v_fma_f32 v80, v84, v80, v94
	v_fma_f32 v81, v85, v81, v95
	v_mul_f32_e64 v78, v98, v78
	v_mul_f32_e64 v79, v99, v79
	v_mul_f32_e64 v80, v100, v80
	v_mul_f32_e64 v81, v101, v81
	v_cvt_pk_bf16_f32 v78, v78, v79
	v_cvt_pk_bf16_f32 v79, v80, v81
	global_store_dwordx2 v[86:87], v[78:79], off offset:128
	global_load_dwordx4 v[78:81], v[116:117], off offset:320
	s_nop 0
	global_load_dwordx4 v[92:95], v[118:119], off offset:320
	global_load_dwordx2 v[82:83], v[86:87], off offset:192
	s_waitcnt vmcnt(4)
	v_lshlrev_b32_e32 v84, 16, v96
	v_and_b32_e32 v85, 0xffff0000, v96
	v_lshlrev_b32_e32 v96, 16, v97
	v_and_b32_e32 v97, 0xffff0000, v97
	v_mul_f32_e32 v89, 0xbfb8aa3b, v84
	v_mul_f32_e32 v98, 0xbfb8aa3b, v85
	v_mul_f32_e32 v99, 0xbfb8aa3b, v96
	v_mul_f32_e32 v100, 0xbfb8aa3b, v97
	v_exp_f32_e32 v89, v89
	v_exp_f32_e32 v98, v98
	v_exp_f32_e32 v99, v99
	v_exp_f32_e32 v100, v100
	v_add_f32_e32 v89, 1.0, v89
	v_add_f32_e32 v101, 1.0, v98
	v_add_f32_e32 v102, 1.0, v99
	v_add_f32_e32 v103, 1.0, v100
	v_rcp_f32_e32 v98, v89
	v_rcp_f32_e32 v99, v101
	v_rcp_f32_e32 v100, v102
	v_rcp_f32_e32 v101, v103
	v_mul_f32_e64 v74, v74, v88
	v_mul_f32_e64 v75, v75, v88
	v_mul_f32_e64 v76, v76, v88
	v_mul_f32_e64 v77, v77, v88
	v_mul_f32_e64 v84, v98, v84
	v_mul_f32_e64 v85, v99, v85
	v_mul_f32_e64 v96, v100, v96
	v_mul_f32_e64 v97, v101, v97
	s_waitcnt vmcnt(1)
	v_fma_f32 v74, v74, v78, v92
	v_fma_f32 v75, v75, v79, v93
	v_fma_f32 v76, v76, v80, v94
	v_fma_f32 v77, v77, v81, v95
	v_mul_f32_e64 v74, v84, v74
	v_mul_f32_e64 v75, v85, v75
	v_mul_f32_e64 v76, v96, v76
	v_mul_f32_e64 v77, v97, v77
	v_cvt_pk_bf16_f32 v74, v74, v75
	v_cvt_pk_bf16_f32 v75, v76, v77
	global_store_dwordx2 v[86:87], v[74:75], off offset:160
	global_load_dwordx4 v[74:77], v[116:117], off offset:384
	s_nop 0
	global_load_dwordx4 v[78:81], v[118:119], off offset:384
	global_load_dwordx2 v[84:85], v[86:87], off offset:224
	s_waitcnt vmcnt(4)
	v_lshlrev_b32_e32 v92, 16, v82
	v_and_b32_e32 v93, 0xffff0000, v82
	v_lshlrev_b32_e32 v82, 16, v83
	v_and_b32_e32 v83, 0xffff0000, v83
	v_mul_f32_e32 v89, 0xbfb8aa3b, v92
	v_mul_f32_e32 v94, 0xbfb8aa3b, v93
	v_mul_f32_e32 v95, 0xbfb8aa3b, v82
	v_mul_f32_e32 v96, 0xbfb8aa3b, v83
	v_exp_f32_e32 v89, v89
	v_exp_f32_e32 v94, v94
	v_exp_f32_e32 v95, v95
	v_exp_f32_e32 v96, v96
	v_add_f32_e32 v89, 1.0, v89
	v_add_f32_e32 v97, 1.0, v94
	v_add_f32_e32 v98, 1.0, v95
	v_add_f32_e32 v99, 1.0, v96
	v_rcp_f32_e32 v94, v89
	v_rcp_f32_e32 v95, v97
	v_rcp_f32_e32 v96, v98
	v_rcp_f32_e32 v97, v99
	v_mul_f32_e64 v70, v70, v88
	v_mul_f32_e64 v71, v71, v88
	v_mul_f32_e64 v72, v72, v88
	v_mul_f32_e64 v73, v73, v88
	v_mul_f32_e64 v92, v94, v92
	v_mul_f32_e64 v93, v95, v93
	v_mul_f32_e64 v82, v96, v82
	v_mul_f32_e64 v83, v97, v83
	v_mul_f32_e64 v66, v66, v88
	v_mul_f32_e64 v67, v67, v88
	v_mul_f32_e64 v68, v68, v88
	v_mul_f32_e64 v69, v69, v88
	s_waitcnt vmcnt(1)
	v_fma_f32 v70, v70, v74, v78
	v_fma_f32 v71, v71, v75, v79
	v_fma_f32 v72, v72, v76, v80
	v_fma_f32 v73, v73, v77, v81
	v_mul_f32_e64 v70, v92, v70
	v_mul_f32_e64 v71, v93, v71
	v_mul_f32_e64 v72, v82, v72
	v_mul_f32_e64 v73, v83, v73
	v_cvt_pk_bf16_f32 v70, v70, v71
	v_cvt_pk_bf16_f32 v71, v72, v73
	global_store_dwordx2 v[86:87], v[70:71], off offset:192
	global_load_dwordx4 v[70:73], v[116:117], off offset:448
	s_nop 0
	global_load_dwordx4 v[74:77], v[118:119], off offset:448
	s_waitcnt vmcnt(3)
	v_lshlrev_b32_e32 v78, 16, v84
	v_and_b32_e32 v79, 0xffff0000, v84
	v_lshlrev_b32_e32 v80, 16, v85
	v_and_b32_e32 v81, 0xffff0000, v85
	v_mul_f32_e32 v82, 0xbfb8aa3b, v78
	v_mul_f32_e32 v83, 0xbfb8aa3b, v79
	v_mul_f32_e32 v84, 0xbfb8aa3b, v80
	v_mul_f32_e32 v85, 0xbfb8aa3b, v81
	v_exp_f32_e32 v82, v82
	v_exp_f32_e32 v83, v83
	v_exp_f32_e32 v84, v84
	v_exp_f32_e32 v85, v85
	v_add_f32_e32 v82, 1.0, v82
	v_add_f32_e32 v83, 1.0, v83
	v_add_f32_e32 v84, 1.0, v84
	v_add_f32_e32 v85, 1.0, v85
	v_rcp_f32_e32 v82, v82
	v_rcp_f32_e32 v83, v83
	v_rcp_f32_e32 v84, v84
	v_rcp_f32_e32 v85, v85
	v_mul_f32_e64 v78, v82, v78
	v_mul_f32_e64 v79, v83, v79
	v_mul_f32_e64 v80, v84, v80
	v_mul_f32_e64 v81, v85, v81
	s_waitcnt vmcnt(0)
	v_fma_f32 v66, v66, v70, v74
	v_fma_f32 v67, v67, v71, v75
	v_fma_f32 v68, v68, v72, v76
	v_fma_f32 v69, v69, v73, v77
	v_mul_f32_e64 v66, v78, v66
	v_mul_f32_e64 v67, v79, v67
	v_mul_f32_e64 v68, v80, v68
	v_mul_f32_e64 v69, v81, v69
	v_cvt_pk_bf16_f32 v66, v66, v67
	v_cvt_pk_bf16_f32 v67, v68, v69
	global_store_dwordx2 v[86:87], v[66:67], off offset:224
	s_cbranch_vccz .LBB0_1084
	s_add_i32 s6, s6, s82
	s_cmpk_gt_i32 s6, 0x1ff
	s_barrier
	s_cbranch_scc0 .LBB0_1083
